# K-loop tails: loop-carried SALU (counter, pointer increments, exit compare) hoisted from after the loop-back barrier into the last MFMA block's shadow; only the branch follows the barrier (7 loops)
# speedup vs baseline: 1.0098x; 1.0098x over previous
; #define G8_STA(bufoff, ptr, sg, h) G8_STAGE1(bufoff, (ptr) + (h) * ((sg) ? hA1 : hA0), ((sg) ? voffA1 : voffA0), ((sg) ? r64A1 : r64A0))
; #define G8_STB(bufoff, ptr, sg, h) G8_STAGE1(bufoff, (ptr) + (h) * ((sg) ? hB1 : hB0), ((sg) ? voffB1 : voffB0), ((sg) ? r64B1 : r64B0))
; #define G8_LDA(dst, b, h) do { _Pragma("unroll") for (int m = 0; m < 4; ++m) _Pragma("unroll") for (int k = 0; k < 2; ++k) dst[m][k] = *(const LAS bf16x8*)(lds + G8_SA(b, h) + aoff + m * 2048 + k * 1024); } while (0)
; #define G8_LDB(dst, b, h) do { _Pragma("unroll") for (int n = 0; n < 2; ++n) _Pragma("unroll") for (int k = 0; k < 2; ++k) dst[n][k] = *(const LAS bf16x8*)(lds + G8_SB(b, h) + boff + n * 2048 + k * 1024); } while (0)
; #define G8_MMA(ai, bj, At, Bt) do { __builtin_amdgcn_s_setprio(1); _Pragma("unroll") for (int m = 0; m < 4; ++m) _Pragma("unroll") for (int n = 0; n < 2; ++n) _Pragma("unroll") for (int k = 0; k < 2; ++k) \
;         acc[ai][bj][m][n] = __builtin_amdgcn_mfma_f32_16x16x32_bf16(Bt[n][k], At[m][k], acc[ai][bj][m][n], 0, 0, 0); __builtin_amdgcn_s_setprio(0); } while (0)
; #define G8_WAIT_V(n) asm volatile("s_waitcnt vmcnt(" #n ")" ::: "memory")
; #define G8_WAIT_L(n) asm volatile("s_waitcnt lgkmcnt(" #n ")" ::: "memory")
; #define G8_BAR __builtin_amdgcn_s_barrier()
; #define G8_SCHED __builtin_amdgcn_sched_barrier(0)
; template <class P>
; __device__ __forceinline__ void gemm_phase(LAS unsigned char* lds, const P& p, const int G, const int c) {
;     ...
;             G8_LDB(B0, 1, 0); G8_LDB(B1, 1, 1); G8_SCHED; G8_LDA(At, 1, 0); G8_STA(G8_SA(0, 1), a2, sg2, 1);
;             G8_WAIT_V(8); G8_WAIT_L(0); G8_BAR; G8_MMA(0, 0, At, B0); G8_MMA(0, 1, At, B1); G8_BAR; G8_SCHED;
;             G8_LDA(At, 1, 1); G8_STB(G8_SB(1, 0), b3, sg2, 0); G8_STB(G8_SB(1, 1), b3, sg2, 1); G8_STA(G8_SA(1, 0), a3, sg2, 0);
;             G8_WAIT_V(8); G8_WAIT_L(0); G8_BAR; G8_MMA(1, 0, At, B0); G8_MMA(1, 1, At, B1); G8_BAR; G8_SCHED;
;         }
.Lmid_155:
	s_barrier
	s_add_i32 s53, 0, 0x18000
	v_add_u32_e32 v68, s53, v152
	s_add_i32 s56, 0, 0x1c000
	ds_read_b128 v[78:81], v68
	ds_read_b128 v[118:121], v68 offset:1024
	ds_read_b128 v[176:179], v68 offset:2048
	ds_read_b128 v[180:183], v68 offset:3072
	v_add_u32_e32 v68, s56, v152
	ds_read_b128 v[184:187], v68
	ds_read_b128 v[188:191], v68 offset:1024
	ds_read_b128 v[192:195], v68 offset:2048
	ds_read_b128 v[196:199], v68 offset:3072
	s_mov_b32 m0, s34
	v_lshl_add_u64 v[68:69], v[236:237], 0, s[6:7]
	ds_read_b128 v[200:203], v175 offset:32768
	ds_read_b128 v[204:207], v175 offset:33792
	ds_read_b128 v[210:213], v175 offset:34816
	ds_read_b128 v[214:217], v175 offset:35840
	ds_read_b128 v[218:221], v175 offset:36864
	ds_read_b128 v[222:225], v175 offset:37888
	ds_read_b128 v[226:229], v175 offset:38912
	ds_read_b128 v[230:233], v175 offset:39936
	global_load_lds_dwordx4 v[68:69], off
	v_lshl_add_u64 v[68:69], v[236:237], 0, s[8:9]
	s_mov_b32 m0, s35
	s_nop 0
	global_load_lds_dwordx4 v[68:69], off
	s_waitcnt vmcnt(8)
	s_waitcnt lgkmcnt(0)
	s_barrier
	s_waitcnt lgkmcnt(0)
	v_mfma_f32_16x16x32_bf16 v[98:101], v[78:81], v[200:203], v[98:101]
	v_mfma_f32_16x16x32_bf16 v[138:141], v[176:179], v[200:203], v[138:141]
	v_mfma_f32_16x16x32_bf16 v[68:71], v[78:81], v[210:213], v[70:73]
	v_mfma_f32_16x16x32_bf16 v[114:117], v[176:179], v[210:213], v[114:117]
	v_mfma_f32_16x16x32_bf16 v[46:49], v[78:81], v[218:221], v[46:49]
	v_mfma_f32_16x16x32_bf16 v[110:113], v[176:179], v[218:221], v[110:113]
	v_mfma_f32_16x16x32_bf16 v[38:41], v[78:81], v[226:229], v[38:41]
	v_mfma_f32_16x16x32_bf16 v[130:133], v[176:179], v[226:229], v[130:133]
	v_mfma_f32_16x16x32_bf16 v[98:101], v[118:121], v[204:207], v[98:101]
	v_mfma_f32_16x16x32_bf16 v[138:141], v[180:183], v[204:207], v[138:141]
	v_mfma_f32_16x16x32_bf16 v[70:73], v[118:121], v[214:217], v[68:71]
	v_mfma_f32_16x16x32_bf16 v[114:117], v[180:183], v[214:217], v[114:117]
	v_mfma_f32_16x16x32_bf16 v[46:49], v[118:121], v[222:225], v[46:49]
	v_mfma_f32_16x16x32_bf16 v[110:113], v[180:183], v[222:225], v[110:113]
	v_mfma_f32_16x16x32_bf16 v[38:41], v[118:121], v[230:233], v[38:41]
	v_mfma_f32_16x16x32_bf16 v[130:133], v[180:183], v[230:233], v[130:133]
	v_mfma_f32_16x16x32_bf16 v[134:137], v[184:187], v[200:203], v[134:137]
	v_mfma_f32_16x16x32_bf16 v[74:77], v[192:195], v[200:203], v[74:77]
	v_mfma_f32_16x16x32_bf16 v[106:109], v[184:187], v[210:213], v[106:109]
	v_mfma_f32_16x16x32_bf16 v[50:53], v[192:195], v[210:213], v[50:53]
	v_mfma_f32_16x16x32_bf16 v[102:105], v[184:187], v[218:221], v[102:105]
	v_mfma_f32_16x16x32_bf16 v[42:45], v[192:195], v[218:221], v[42:45]
	v_mfma_f32_16x16x32_bf16 v[126:129], v[184:187], v[226:229], v[126:129]
	v_mfma_f32_16x16x32_bf16 v[34:37], v[192:195], v[226:229], v[34:37]
	v_mfma_f32_16x16x32_bf16 v[134:137], v[188:191], v[204:207], v[134:137]
	v_mfma_f32_16x16x32_bf16 v[74:77], v[196:199], v[204:207], v[74:77]
	v_mfma_f32_16x16x32_bf16 v[106:109], v[188:191], v[214:217], v[106:109]
	v_mfma_f32_16x16x32_bf16 v[50:53], v[196:199], v[214:217], v[50:53]
	v_mfma_f32_16x16x32_bf16 v[102:105], v[188:191], v[222:225], v[102:105]
	v_mfma_f32_16x16x32_bf16 v[42:45], v[196:199], v[222:225], v[42:45]
	v_mfma_f32_16x16x32_bf16 v[126:129], v[188:191], v[230:233], v[126:129]
	v_mfma_f32_16x16x32_bf16 v[34:37], v[196:199], v[230:233], v[34:37]
	s_barrier
	s_add_i32 s53, s53, s2
	v_lshl_add_u64 v[68:69], v[234:235], 0, s[12:13]
	s_mov_b32 m0, s53
	ds_read_b128 v[200:203], v175 offset:49152
	ds_read_b128 v[204:207], v175 offset:50176
	ds_read_b128 v[210:213], v175 offset:51200
	ds_read_b128 v[214:217], v175 offset:52224
	ds_read_b128 v[218:221], v175 offset:53248
	ds_read_b128 v[222:225], v175 offset:54272
	ds_read_b128 v[226:229], v175 offset:55296
	ds_read_b128 v[230:233], v175 offset:56320
	global_load_lds_dwordx4 v[68:69], off
	v_lshl_add_u64 v[68:69], v[234:235], 0, s[14:15]
	s_add_i32 m0, s53, 0x2000
	s_add_i32 s53, s56, s2
	global_load_lds_dwordx4 v[68:69], off
	v_lshl_add_u64 v[68:69], v[234:235], 0, s[22:23]
	s_mov_b32 m0, s53
	s_nop 0
	global_load_lds_dwordx4 v[68:69], off
	v_lshl_add_u64 v[68:69], v[234:235], 0, s[36:37]
	s_add_i32 m0, s53, 0x2000
	s_nop 0
	global_load_lds_dwordx4 v[68:69], off
	v_lshl_add_u64 v[68:69], v[236:237], 0, s[16:17]
	s_mov_b32 m0, s47
	s_nop 0
	global_load_lds_dwordx4 v[68:69], off
	v_lshl_add_u64 v[68:69], v[236:237], 0, s[20:21]
	s_mov_b32 m0, s48
	s_nop 0
	global_load_lds_dwordx4 v[68:69], off
	s_waitcnt vmcnt(8)
	s_waitcnt lgkmcnt(0)
	s_barrier
	s_waitcnt lgkmcnt(0)
	v_mfma_f32_16x16x32_bf16 v[30:33], v[78:81], v[200:203], v[30:33]
	v_mfma_f32_16x16x32_bf16 v[122:125], v[176:179], v[200:203], v[122:125]
	v_mfma_f32_16x16x32_bf16 v[22:25], v[78:81], v[210:213], v[22:25]
	v_mfma_f32_16x16x32_bf16 v[94:97], v[176:179], v[210:213], v[94:97]
	s_add_i32 s52, s52, 2
	v_mfma_f32_16x16x32_bf16 v[14:17], v[78:81], v[218:221], v[14:17]
	s_add_u32 s28, s28, 0x200000
	v_mfma_f32_16x16x32_bf16 v[90:93], v[176:179], v[218:221], v[90:93]
	s_addc_u32 s29, s29, 0
	v_mfma_f32_16x16x32_bf16 v[6:9], v[78:81], v[226:229], v[6:9]
	s_add_u32 s84, s84, 0x820000
	v_mfma_f32_16x16x32_bf16 v[56:59], v[176:179], v[226:229], v[56:59]
	s_addc_u32 s85, s85, 0
	v_mfma_f32_16x16x32_bf16 v[30:33], v[118:121], v[204:207], v[30:33]
	s_cmp_gt_u32 s52, 13
	v_mfma_f32_16x16x32_bf16 v[122:125], v[180:183], v[204:207], v[122:125]
	v_mfma_f32_16x16x32_bf16 v[22:25], v[118:121], v[214:217], v[22:25]
	v_mfma_f32_16x16x32_bf16 v[94:97], v[180:183], v[214:217], v[94:97]
	v_mfma_f32_16x16x32_bf16 v[14:17], v[118:121], v[222:225], v[14:17]
	v_mfma_f32_16x16x32_bf16 v[90:93], v[180:183], v[222:225], v[90:93]
	v_mfma_f32_16x16x32_bf16 v[6:9], v[118:121], v[230:233], v[6:9]
	v_mfma_f32_16x16x32_bf16 v[78:81], v[180:183], v[230:233], v[56:59]
	v_mfma_f32_16x16x32_bf16 v[56:59], v[184:187], v[200:203], v[60:63]
	v_mfma_f32_16x16x32_bf16 v[118:121], v[188:191], v[204:207], v[56:59]
	v_mfma_f32_16x16x32_bf16 v[56:59], v[184:187], v[210:213], v[86:89]
	v_mfma_f32_16x16x32_bf16 v[86:89], v[188:191], v[214:217], v[56:59]
	v_mfma_f32_16x16x32_bf16 v[56:59], v[184:187], v[218:221], v[82:85]
	v_mfma_f32_16x16x32_bf16 v[26:29], v[192:195], v[200:203], v[26:29]
	v_mfma_f32_16x16x32_bf16 v[18:21], v[192:195], v[210:213], v[18:21]
	v_mfma_f32_16x16x32_bf16 v[82:85], v[188:191], v[222:225], v[56:59]
	v_mfma_f32_16x16x32_bf16 v[10:13], v[192:195], v[218:221], v[10:13]
	v_mfma_f32_16x16x32_bf16 v[56:59], v[184:187], v[226:229], v[64:67]
	v_mfma_f32_16x16x32_bf16 v[2:5], v[192:195], v[226:229], v[2:5]
	v_mfma_f32_16x16x32_bf16 v[26:29], v[196:199], v[204:207], v[26:29]
	v_mfma_f32_16x16x32_bf16 v[18:21], v[196:199], v[214:217], v[18:21]
	v_mfma_f32_16x16x32_bf16 v[10:13], v[196:199], v[222:225], v[10:13]
	v_mfma_f32_16x16x32_bf16 v[66:69], v[188:191], v[230:233], v[56:59]
	v_mfma_f32_16x16x32_bf16 v[2:5], v[196:199], v[230:233], v[2:5]
	s_barrier
	s_cbranch_scc0 .LBB0_155
	s_and_b64 vcc, exec, s[38:39]
	s_cbranch_vccz .LBB0_158
	s_barrier

; #define G8_STA(bufoff, ptr, sg, h) G8_STAGE1(bufoff, (ptr) + (h) * ((sg) ? hA1 : hA0), ((sg) ? voffA1 : voffA0), ((sg) ? r64A1 : r64A0))
; #define G8_STB(bufoff, ptr, sg, h) G8_STAGE1(bufoff, (ptr) + (h) * ((sg) ? hB1 : hB0), ((sg) ? voffB1 : voffB0), ((sg) ? r64B1 : r64B0))
; #define G8_LDA(dst, b, h) do { _Pragma("unroll") for (int m = 0; m < 4; ++m) _Pragma("unroll") for (int k = 0; k < 2; ++k) dst[m][k] = *(const LAS bf16x8*)(lds + G8_SA(b, h) + aoff + m * 2048 + k * 1024); } while (0)
; #define G8_LDB(dst, b, h) do { _Pragma("unroll") for (int n = 0; n < 2; ++n) _Pragma("unroll") for (int k = 0; k < 2; ++k) dst[n][k] = *(const LAS bf16x8*)(lds + G8_SB(b, h) + boff + n * 2048 + k * 1024); } while (0)
; #define G8_MMA(ai, bj, At, Bt) do { __builtin_amdgcn_s_setprio(1); _Pragma("unroll") for (int m = 0; m < 4; ++m) _Pragma("unroll") for (int n = 0; n < 2; ++n) _Pragma("unroll") for (int k = 0; k < 2; ++k) \
;         acc[ai][bj][m][n] = __builtin_amdgcn_mfma_f32_16x16x32_bf16(Bt[n][k], At[m][k], acc[ai][bj][m][n], 0, 0, 0); __builtin_amdgcn_s_setprio(0); } while (0)
; #define G8_WAIT_V(n) asm volatile("s_waitcnt vmcnt(" #n ")" ::: "memory")
; #define G8_WAIT_L(n) asm volatile("s_waitcnt lgkmcnt(" #n ")" ::: "memory")
; #define G8_BAR __builtin_amdgcn_s_barrier()
; #define G8_SCHED __builtin_amdgcn_sched_barrier(0)
; template <class P>
; __device__ __forceinline__ void gemm_phase(LAS unsigned char* lds, const P& p, const int G, const int c) {
;     ...
;             G8_LDB(B0, 1, 0); G8_LDB(B1, 1, 1); G8_SCHED; G8_LDA(At, 1, 0); G8_STA(G8_SA(0, 1), a2, sg2, 1);
;             G8_WAIT_V(8); G8_WAIT_L(0); G8_BAR; G8_MMA(0, 0, At, B0); G8_MMA(0, 1, At, B1); G8_BAR; G8_SCHED;
;             G8_LDA(At, 1, 1); G8_STB(G8_SB(1, 0), b3, sg2, 0); G8_STB(G8_SB(1, 1), b3, sg2, 1); G8_STA(G8_SA(1, 0), a3, sg2, 0);
;             G8_WAIT_V(8); G8_WAIT_L(0); G8_BAR; G8_MMA(1, 0, At, B0); G8_MMA(1, 1, At, B1); G8_BAR; G8_SCHED;
;         }
.Lmid_277:
	s_barrier
	s_add_i32 s28, 0, 0x18000
	s_add_i32 s29, 0, 0x1c000
	v_add_u32_e32 v176, s28, v1
	v_add_u32_e32 v192, s29, v1
	ds_read_b128 v[132:135], v176
	ds_read_b128 v[136:139], v176 offset:1024
	ds_read_b128 v[140:143], v176 offset:2048
	ds_read_b128 v[176:179], v176 offset:3072
	ds_read_b128 v[180:183], v192
	ds_read_b128 v[184:187], v192 offset:1024
	ds_read_b128 v[188:191], v192 offset:2048
	ds_read_b128 v[192:195], v192 offset:3072
	s_mov_b32 m0, s34
	v_lshl_add_u64 v[232:233], v[230:231], 0, s[12:13]
	ds_read_b128 v[196:199], v175 offset:32768
	ds_read_b128 v[200:203], v175 offset:33792
	ds_read_b128 v[204:207], v175 offset:34816
	ds_read_b128 v[210:213], v175 offset:35840
	ds_read_b128 v[214:217], v175 offset:36864
	ds_read_b128 v[218:221], v175 offset:37888
	ds_read_b128 v[222:225], v175 offset:38912
	ds_read_b128 v[226:229], v175 offset:39936
	global_load_lds_dwordx4 v[232:233], off
	v_lshl_add_u64 v[232:233], v[230:231], 0, s[14:15]
	s_mov_b32 m0, s35
	s_nop 0
	global_load_lds_dwordx4 v[232:233], off
	s_waitcnt vmcnt(8)
	s_waitcnt lgkmcnt(0)
	s_barrier
	s_waitcnt lgkmcnt(0)
	v_mfma_f32_16x16x32_bf16 v[126:129], v[132:135], v[196:199], v[126:129]
	v_mfma_f32_16x16x32_bf16 v[122:125], v[140:143], v[196:199], v[122:125]
	v_mfma_f32_16x16x32_bf16 v[118:121], v[132:135], v[204:207], v[118:121]
	v_mfma_f32_16x16x32_bf16 v[114:117], v[140:143], v[204:207], v[114:117]
	v_mfma_f32_16x16x32_bf16 v[106:109], v[132:135], v[214:217], v[106:109]
	v_mfma_f32_16x16x32_bf16 v[98:101], v[140:143], v[214:217], v[98:101]
	v_mfma_f32_16x16x32_bf16 v[94:97], v[132:135], v[222:225], v[94:97]
	v_mfma_f32_16x16x32_bf16 v[86:89], v[140:143], v[222:225], v[86:89]
	v_mfma_f32_16x16x32_bf16 v[126:129], v[136:139], v[200:203], v[126:129]
	v_mfma_f32_16x16x32_bf16 v[122:125], v[176:179], v[200:203], v[122:125]
	v_mfma_f32_16x16x32_bf16 v[118:121], v[136:139], v[210:213], v[118:121]
	v_mfma_f32_16x16x32_bf16 v[114:117], v[176:179], v[210:213], v[114:117]
	v_mfma_f32_16x16x32_bf16 v[106:109], v[136:139], v[218:221], v[106:109]
	v_mfma_f32_16x16x32_bf16 v[98:101], v[176:179], v[218:221], v[98:101]
	v_mfma_f32_16x16x32_bf16 v[94:97], v[136:139], v[226:229], v[94:97]
	v_mfma_f32_16x16x32_bf16 v[86:89], v[176:179], v[226:229], v[86:89]
	v_mfma_f32_16x16x32_bf16 v[110:113], v[180:183], v[196:199], v[110:113]
	v_mfma_f32_16x16x32_bf16 v[102:105], v[188:191], v[196:199], v[102:105]
	v_mfma_f32_16x16x32_bf16 v[90:93], v[180:183], v[204:207], v[90:93]
	v_mfma_f32_16x16x32_bf16 v[82:85], v[188:191], v[204:207], v[82:85]
	v_mfma_f32_16x16x32_bf16 v[78:81], v[180:183], v[214:217], v[78:81]
	v_mfma_f32_16x16x32_bf16 v[74:77], v[188:191], v[214:217], v[74:77]
	v_mfma_f32_16x16x32_bf16 v[70:73], v[180:183], v[222:225], v[70:73]
	v_mfma_f32_16x16x32_bf16 v[66:69], v[188:191], v[222:225], v[66:69]
	v_mfma_f32_16x16x32_bf16 v[110:113], v[184:187], v[200:203], v[110:113]
	v_mfma_f32_16x16x32_bf16 v[102:105], v[192:195], v[200:203], v[102:105]
	v_mfma_f32_16x16x32_bf16 v[90:93], v[184:187], v[210:213], v[90:93]
	v_mfma_f32_16x16x32_bf16 v[82:85], v[192:195], v[210:213], v[82:85]
	v_mfma_f32_16x16x32_bf16 v[78:81], v[184:187], v[218:221], v[78:81]
	v_mfma_f32_16x16x32_bf16 v[74:77], v[192:195], v[218:221], v[74:77]
	v_mfma_f32_16x16x32_bf16 v[70:73], v[184:187], v[226:229], v[70:73]
	v_mfma_f32_16x16x32_bf16 v[66:69], v[192:195], v[226:229], v[66:69]
	s_barrier
	s_add_i32 s28, s28, s26
	v_lshl_add_u64 v[232:233], v[144:145], 0, s[20:21]
	s_mov_b32 m0, s28
	ds_read_b128 v[196:199], v175 offset:49152
	ds_read_b128 v[200:203], v175 offset:50176
	ds_read_b128 v[204:207], v175 offset:51200
	ds_read_b128 v[210:213], v175 offset:52224
	ds_read_b128 v[214:217], v175 offset:53248
	ds_read_b128 v[218:221], v175 offset:54272
	ds_read_b128 v[222:225], v175 offset:55296
	ds_read_b128 v[226:229], v175 offset:56320
	global_load_lds_dwordx4 v[232:233], off
	v_lshl_add_u64 v[232:233], v[144:145], 0, s[22:23]
	s_add_i32 m0, s28, 0x2000
	s_add_i32 s28, s29, s26
	global_load_lds_dwordx4 v[232:233], off
	v_lshl_add_u64 v[232:233], v[144:145], 0, s[40:41]
	s_mov_b32 m0, s28
	v_lshl_add_u64 v[144:145], v[144:145], 0, s[42:43]
	global_load_lds_dwordx4 v[232:233], off
	s_add_i32 m0, s28, 0x2000
	s_nop 0
	global_load_lds_dwordx4 v[144:145], off
	v_lshl_add_u64 v[144:145], v[230:231], 0, s[36:37]
	s_mov_b32 m0, s50
	s_nop 0
	global_load_lds_dwordx4 v[144:145], off
	v_lshl_add_u64 v[144:145], v[230:231], 0, s[38:39]
	s_mov_b32 m0, s51
	s_nop 0
	global_load_lds_dwordx4 v[144:145], off
	s_waitcnt vmcnt(8)
	s_waitcnt lgkmcnt(0)
	s_barrier
	s_waitcnt lgkmcnt(0)
	v_mfma_f32_16x16x32_bf16 v[62:65], v[132:135], v[196:199], v[62:65]
	v_mfma_f32_16x16x32_bf16 v[58:61], v[140:143], v[196:199], v[58:61]
	v_mfma_f32_16x16x32_bf16 v[54:57], v[132:135], v[204:207], v[54:57]
	v_mfma_f32_16x16x32_bf16 v[50:53], v[140:143], v[204:207], v[50:53]
	s_add_u32 s19, s19, 0x40000
	v_mfma_f32_16x16x32_bf16 v[46:49], v[132:135], v[214:217], v[46:49]
	s_addc_u32 s49, s49, 0
	v_mfma_f32_16x16x32_bf16 v[38:41], v[140:143], v[214:217], v[38:41]
	s_add_u32 s76, s76, 0x820000
	v_mfma_f32_16x16x32_bf16 v[30:33], v[132:135], v[222:225], v[30:33]
	s_addc_u32 s77, s77, 0
	v_mfma_f32_16x16x32_bf16 v[22:25], v[140:143], v[222:225], v[22:25]
	s_cmp_ge_u32 s57, s5
	v_mfma_f32_16x16x32_bf16 v[62:65], v[136:139], v[200:203], v[62:65]
	v_mfma_f32_16x16x32_bf16 v[58:61], v[176:179], v[200:203], v[58:61]
	v_mfma_f32_16x16x32_bf16 v[54:57], v[136:139], v[210:213], v[54:57]
	v_mfma_f32_16x16x32_bf16 v[50:53], v[176:179], v[210:213], v[50:53]
	v_mfma_f32_16x16x32_bf16 v[46:49], v[136:139], v[218:221], v[46:49]
	v_mfma_f32_16x16x32_bf16 v[38:41], v[176:179], v[218:221], v[38:41]
	v_mfma_f32_16x16x32_bf16 v[30:33], v[136:139], v[226:229], v[30:33]
	v_mfma_f32_16x16x32_bf16 v[22:25], v[176:179], v[226:229], v[22:25]
	v_mfma_f32_16x16x32_bf16 v[42:45], v[180:183], v[196:199], v[42:45]
	v_mfma_f32_16x16x32_bf16 v[34:37], v[188:191], v[196:199], v[34:37]
	v_mfma_f32_16x16x32_bf16 v[26:29], v[180:183], v[204:207], v[26:29]
	v_mfma_f32_16x16x32_bf16 v[18:21], v[188:191], v[204:207], v[18:21]
	v_mfma_f32_16x16x32_bf16 v[14:17], v[180:183], v[214:217], v[14:17]
	v_mfma_f32_16x16x32_bf16 v[10:13], v[188:191], v[214:217], v[10:13]
	v_mfma_f32_16x16x32_bf16 v[6:9], v[180:183], v[222:225], v[6:9]
	v_mfma_f32_16x16x32_bf16 v[2:5], v[188:191], v[222:225], v[2:5]
	v_mfma_f32_16x16x32_bf16 v[42:45], v[184:187], v[200:203], v[42:45]
	v_mfma_f32_16x16x32_bf16 v[34:37], v[192:195], v[200:203], v[34:37]
	v_mfma_f32_16x16x32_bf16 v[26:29], v[184:187], v[210:213], v[26:29]
	v_mfma_f32_16x16x32_bf16 v[18:21], v[192:195], v[210:213], v[18:21]
	v_mfma_f32_16x16x32_bf16 v[14:17], v[184:187], v[218:221], v[14:17]
	v_mfma_f32_16x16x32_bf16 v[10:13], v[192:195], v[218:221], v[10:13]
	v_mfma_f32_16x16x32_bf16 v[6:9], v[184:187], v[226:229], v[6:9]
	v_mfma_f32_16x16x32_bf16 v[2:5], v[192:195], v[226:229], v[2:5]
	s_barrier
	s_cbranch_scc1 .LBB0_282

; #define G8_STA(bufoff, ptr, sg, h) G8_STAGE1(bufoff, (ptr) + (h) * ((sg) ? hA1 : hA0), ((sg) ? voffA1 : voffA0), ((sg) ? r64A1 : r64A0))
; #define G8_STB(bufoff, ptr, sg, h) G8_STAGE1(bufoff, (ptr) + (h) * ((sg) ? hB1 : hB0), ((sg) ? voffB1 : voffB0), ((sg) ? r64B1 : r64B0))
; #define G8_LDA(dst, b, h) do { _Pragma("unroll") for (int m = 0; m < 4; ++m) _Pragma("unroll") for (int k = 0; k < 2; ++k) dst[m][k] = *(const LAS bf16x8*)(lds + G8_SA(b, h) + aoff + m * 2048 + k * 1024); } while (0)
; #define G8_LDB(dst, b, h) do { _Pragma("unroll") for (int n = 0; n < 2; ++n) _Pragma("unroll") for (int k = 0; k < 2; ++k) dst[n][k] = *(const LAS bf16x8*)(lds + G8_SB(b, h) + boff + n * 2048 + k * 1024); } while (0)
; #define G8_MMA(ai, bj, At, Bt) do { __builtin_amdgcn_s_setprio(1); _Pragma("unroll") for (int m = 0; m < 4; ++m) _Pragma("unroll") for (int n = 0; n < 2; ++n) _Pragma("unroll") for (int k = 0; k < 2; ++k) \
;         acc[ai][bj][m][n] = __builtin_amdgcn_mfma_f32_16x16x32_bf16(Bt[n][k], At[m][k], acc[ai][bj][m][n], 0, 0, 0); __builtin_amdgcn_s_setprio(0); } while (0)
; #define G8_WAIT_V(n) asm volatile("s_waitcnt vmcnt(" #n ")" ::: "memory")
; #define G8_WAIT_L(n) asm volatile("s_waitcnt lgkmcnt(" #n ")" ::: "memory")
; #define G8_BAR __builtin_amdgcn_s_barrier()
; #define G8_SCHED __builtin_amdgcn_sched_barrier(0)
; template <class P>
; __device__ __forceinline__ void gemm_phase(LAS unsigned char* lds, const P& p, const int G, const int c) {
;     ...
;             G8_LDB(B0, 1, 0); G8_LDB(B1, 1, 1); G8_SCHED; G8_LDA(At, 1, 0); G8_STA(G8_SA(0, 1), a2, sg2, 1);
;             G8_WAIT_V(8); G8_WAIT_L(0); G8_BAR; G8_MMA(0, 0, At, B0); G8_MMA(0, 1, At, B1); G8_BAR; G8_SCHED;
;             G8_LDA(At, 1, 1); G8_STB(G8_SB(1, 0), b3, sg2, 0); G8_STB(G8_SB(1, 1), b3, sg2, 1); G8_STA(G8_SA(1, 0), a3, sg2, 0);
;             G8_WAIT_V(8); G8_WAIT_L(0); G8_BAR; G8_MMA(1, 0, At, B0); G8_MMA(1, 1, At, B1); G8_BAR; G8_SCHED;
;         }
.Lmid_410:
	s_barrier
	s_add_i32 s28, 0, 0x18000
	v_add_u32_e32 v130, s28, v137
	s_add_i32 s29, 0, 0x1c000
	ds_read_b128 v[142:145], v130
	ds_read_b128 v[146:149], v130 offset:1024
	ds_read_b128 v[162:165], v130 offset:2048
	ds_read_b128 v[166:169], v130 offset:3072
	v_add_u32_e32 v130, s29, v137
	ds_read_b128 v[170:173], v130
	ds_read_b128 v[174:177], v130 offset:1024
	ds_read_b128 v[178:181], v130 offset:2048
	ds_read_b128 v[182:185], v130 offset:3072
	s_mov_b32 m0, s34
	v_lshl_add_u64 v[224:225], v[222:223], 0, s[10:11]
	ds_read_b128 v[186:189], v158 offset:32768
	ds_read_b128 v[190:193], v158 offset:33792
	ds_read_b128 v[194:197], v158 offset:34816
	ds_read_b128 v[198:201], v158 offset:35840
	ds_read_b128 v[202:205], v158 offset:36864
	ds_read_b128 v[210:213], v158 offset:37888
	ds_read_b128 v[214:217], v158 offset:38912
	ds_read_b128 v[218:221], v158 offset:39936
	global_load_lds_dwordx4 v[224:225], off
	v_lshl_add_u64 v[224:225], v[222:223], 0, s[12:13]
	s_mov_b32 m0, s35
	s_nop 0
	global_load_lds_dwordx4 v[224:225], off
	s_waitcnt vmcnt(8)
	s_waitcnt lgkmcnt(0)
	s_barrier
	s_waitcnt lgkmcnt(0)
	v_mfma_f32_16x16x32_bf16 v[126:129], v[142:145], v[186:189], v[126:129]
	v_mfma_f32_16x16x32_bf16 v[122:125], v[162:165], v[186:189], v[122:125]
	v_mfma_f32_16x16x32_bf16 v[110:113], v[142:145], v[194:197], v[110:113]
	v_mfma_f32_16x16x32_bf16 v[106:109], v[162:165], v[194:197], v[106:109]
	v_mfma_f32_16x16x32_bf16 v[94:97], v[142:145], v[202:205], v[94:97]
	v_mfma_f32_16x16x32_bf16 v[90:93], v[162:165], v[202:205], v[90:93]
	v_mfma_f32_16x16x32_bf16 v[78:81], v[142:145], v[214:217], v[78:81]
	v_mfma_f32_16x16x32_bf16 v[74:77], v[162:165], v[214:217], v[74:77]
	v_mfma_f32_16x16x32_bf16 v[126:129], v[146:149], v[190:193], v[126:129]
	v_mfma_f32_16x16x32_bf16 v[122:125], v[166:169], v[190:193], v[122:125]
	v_mfma_f32_16x16x32_bf16 v[110:113], v[146:149], v[198:201], v[110:113]
	v_mfma_f32_16x16x32_bf16 v[106:109], v[166:169], v[198:201], v[106:109]
	v_mfma_f32_16x16x32_bf16 v[94:97], v[146:149], v[210:213], v[94:97]
	v_mfma_f32_16x16x32_bf16 v[90:93], v[166:169], v[210:213], v[90:93]
	v_mfma_f32_16x16x32_bf16 v[78:81], v[146:149], v[218:221], v[78:81]
	v_mfma_f32_16x16x32_bf16 v[74:77], v[166:169], v[218:221], v[74:77]
	v_mfma_f32_16x16x32_bf16 v[118:121], v[170:173], v[186:189], v[118:121]
	v_mfma_f32_16x16x32_bf16 v[114:117], v[178:181], v[186:189], v[114:117]
	v_mfma_f32_16x16x32_bf16 v[102:105], v[170:173], v[194:197], v[102:105]
	v_mfma_f32_16x16x32_bf16 v[98:101], v[178:181], v[194:197], v[98:101]
	v_mfma_f32_16x16x32_bf16 v[86:89], v[170:173], v[202:205], v[86:89]
	v_mfma_f32_16x16x32_bf16 v[82:85], v[178:181], v[202:205], v[82:85]
	v_mfma_f32_16x16x32_bf16 v[70:73], v[170:173], v[214:217], v[70:73]
	v_mfma_f32_16x16x32_bf16 v[66:69], v[178:181], v[214:217], v[66:69]
	v_mfma_f32_16x16x32_bf16 v[118:121], v[174:177], v[190:193], v[118:121]
	v_mfma_f32_16x16x32_bf16 v[114:117], v[182:185], v[190:193], v[114:117]
	v_mfma_f32_16x16x32_bf16 v[102:105], v[174:177], v[198:201], v[102:105]
	v_mfma_f32_16x16x32_bf16 v[98:101], v[182:185], v[198:201], v[98:101]
	v_mfma_f32_16x16x32_bf16 v[86:89], v[174:177], v[210:213], v[86:89]
	v_mfma_f32_16x16x32_bf16 v[82:85], v[182:185], v[210:213], v[82:85]
	v_mfma_f32_16x16x32_bf16 v[70:73], v[174:177], v[218:221], v[70:73]
	v_mfma_f32_16x16x32_bf16 v[66:69], v[182:185], v[218:221], v[66:69]
	s_barrier
	s_add_i32 s28, s28, s26
	v_lshl_add_u64 v[224:225], v[206:207], 0, s[20:21]
	s_mov_b32 m0, s28
	ds_read_b128 v[186:189], v158 offset:49152
	ds_read_b128 v[190:193], v158 offset:50176
	ds_read_b128 v[194:197], v158 offset:51200
	ds_read_b128 v[198:201], v158 offset:52224
	ds_read_b128 v[202:205], v158 offset:53248
	ds_read_b128 v[210:213], v158 offset:54272
	ds_read_b128 v[214:217], v158 offset:55296
	ds_read_b128 v[218:221], v158 offset:56320
	global_load_lds_dwordx4 v[224:225], off
	v_lshl_add_u64 v[224:225], v[206:207], 0, s[22:23]
	s_add_i32 m0, s28, 0x2000
	s_add_i32 s28, s29, s26
	global_load_lds_dwordx4 v[224:225], off
	v_lshl_add_u64 v[224:225], v[206:207], 0, s[40:41]
	s_mov_b32 m0, s28
	v_lshl_add_u64 v[206:207], v[206:207], 0, s[42:43]
	global_load_lds_dwordx4 v[224:225], off
	s_add_i32 m0, s28, 0x2000
	s_nop 0
	global_load_lds_dwordx4 v[206:207], off
	v_lshl_add_u64 v[206:207], v[222:223], 0, s[36:37]
	s_mov_b32 m0, s51
	s_nop 0
	global_load_lds_dwordx4 v[206:207], off
	v_lshl_add_u64 v[206:207], v[222:223], 0, s[38:39]
	s_mov_b32 m0, s64
	s_nop 0
	global_load_lds_dwordx4 v[206:207], off
	s_waitcnt vmcnt(8)
	s_waitcnt lgkmcnt(0)
	s_barrier
	s_waitcnt lgkmcnt(0)
	v_mfma_f32_16x16x32_bf16 v[62:65], v[142:145], v[186:189], v[62:65]
	v_mfma_f32_16x16x32_bf16 v[58:61], v[162:165], v[186:189], v[58:61]
	v_mfma_f32_16x16x32_bf16 v[46:49], v[142:145], v[194:197], v[46:49]
	v_mfma_f32_16x16x32_bf16 v[42:45], v[162:165], v[194:197], v[42:45]
	s_add_u32 s19, s19, 0x100000
	v_mfma_f32_16x16x32_bf16 v[30:33], v[142:145], v[202:205], v[30:33]
	s_addc_u32 s53, s53, 0
	v_mfma_f32_16x16x32_bf16 v[26:29], v[162:165], v[202:205], v[26:29]
	s_add_u32 s70, s70, 0x820000
	v_mfma_f32_16x16x32_bf16 v[14:17], v[142:145], v[214:217], v[14:17]
	s_addc_u32 s71, s71, 0
	v_mfma_f32_16x16x32_bf16 v[10:13], v[162:165], v[214:217], v[10:13]
	s_cmp_ge_u32 s74, s1
	v_mfma_f32_16x16x32_bf16 v[62:65], v[146:149], v[190:193], v[62:65]
	v_mfma_f32_16x16x32_bf16 v[58:61], v[166:169], v[190:193], v[58:61]
	v_mfma_f32_16x16x32_bf16 v[46:49], v[146:149], v[198:201], v[46:49]
	v_mfma_f32_16x16x32_bf16 v[42:45], v[166:169], v[198:201], v[42:45]
	v_mfma_f32_16x16x32_bf16 v[30:33], v[146:149], v[210:213], v[30:33]
	v_mfma_f32_16x16x32_bf16 v[26:29], v[166:169], v[210:213], v[26:29]
	v_mfma_f32_16x16x32_bf16 v[14:17], v[146:149], v[218:221], v[14:17]
	v_mfma_f32_16x16x32_bf16 v[10:13], v[166:169], v[218:221], v[10:13]
	v_mfma_f32_16x16x32_bf16 v[54:57], v[170:173], v[186:189], v[54:57]
	v_mfma_f32_16x16x32_bf16 v[50:53], v[178:181], v[186:189], v[50:53]
	v_mfma_f32_16x16x32_bf16 v[38:41], v[170:173], v[194:197], v[38:41]
	v_mfma_f32_16x16x32_bf16 v[34:37], v[178:181], v[194:197], v[34:37]
	v_mfma_f32_16x16x32_bf16 v[22:25], v[170:173], v[202:205], v[22:25]
	v_mfma_f32_16x16x32_bf16 v[18:21], v[178:181], v[202:205], v[18:21]
	v_mfma_f32_16x16x32_bf16 v[6:9], v[170:173], v[214:217], v[6:9]
	v_mfma_f32_16x16x32_bf16 v[2:5], v[178:181], v[214:217], v[2:5]
	v_mfma_f32_16x16x32_bf16 v[54:57], v[174:177], v[190:193], v[54:57]
	v_mfma_f32_16x16x32_bf16 v[50:53], v[182:185], v[190:193], v[50:53]
	v_mfma_f32_16x16x32_bf16 v[38:41], v[174:177], v[198:201], v[38:41]
	v_mfma_f32_16x16x32_bf16 v[34:37], v[182:185], v[198:201], v[34:37]
	v_mfma_f32_16x16x32_bf16 v[22:25], v[174:177], v[210:213], v[22:25]
	v_mfma_f32_16x16x32_bf16 v[18:21], v[182:185], v[210:213], v[18:21]
	v_mfma_f32_16x16x32_bf16 v[6:9], v[174:177], v[218:221], v[6:9]
	v_mfma_f32_16x16x32_bf16 v[2:5], v[182:185], v[218:221], v[2:5]
	s_barrier
	s_cbranch_scc1 .LBB0_415

; #define G8_STA(bufoff, ptr, sg, h) G8_STAGE1(bufoff, (ptr) + (h) * ((sg) ? hA1 : hA0), ((sg) ? voffA1 : voffA0), ((sg) ? r64A1 : r64A0))
; #define G8_STB(bufoff, ptr, sg, h) G8_STAGE1(bufoff, (ptr) + (h) * ((sg) ? hB1 : hB0), ((sg) ? voffB1 : voffB0), ((sg) ? r64B1 : r64B0))
; #define G8_LDA(dst, b, h) do { _Pragma("unroll") for (int m = 0; m < 4; ++m) _Pragma("unroll") for (int k = 0; k < 2; ++k) dst[m][k] = *(const LAS bf16x8*)(lds + G8_SA(b, h) + aoff + m * 2048 + k * 1024); } while (0)
; #define G8_LDB(dst, b, h) do { _Pragma("unroll") for (int n = 0; n < 2; ++n) _Pragma("unroll") for (int k = 0; k < 2; ++k) dst[n][k] = *(const LAS bf16x8*)(lds + G8_SB(b, h) + boff + n * 2048 + k * 1024); } while (0)
; #define G8_MMA(ai, bj, At, Bt) do { __builtin_amdgcn_s_setprio(1); _Pragma("unroll") for (int m = 0; m < 4; ++m) _Pragma("unroll") for (int n = 0; n < 2; ++n) _Pragma("unroll") for (int k = 0; k < 2; ++k) \
;         acc[ai][bj][m][n] = __builtin_amdgcn_mfma_f32_16x16x32_bf16(Bt[n][k], At[m][k], acc[ai][bj][m][n], 0, 0, 0); __builtin_amdgcn_s_setprio(0); } while (0)
; #define G8_WAIT_V(n) asm volatile("s_waitcnt vmcnt(" #n ")" ::: "memory")
; #define G8_WAIT_L(n) asm volatile("s_waitcnt lgkmcnt(" #n ")" ::: "memory")
; #define G8_BAR __builtin_amdgcn_s_barrier()
; #define G8_SCHED __builtin_amdgcn_sched_barrier(0)
; template <class P>
; __device__ __forceinline__ void gemm_phase(LAS unsigned char* lds, const P& p, const int G, const int c) {
;     ...
;             G8_LDB(B0, 1, 0); G8_LDB(B1, 1, 1); G8_SCHED; G8_LDA(At, 1, 0); G8_STA(G8_SA(0, 1), a2, sg2, 1);
;             G8_WAIT_V(8); G8_WAIT_L(0); G8_BAR; G8_MMA(0, 0, At, B0); G8_MMA(0, 1, At, B1); G8_BAR; G8_SCHED;
;             G8_LDA(At, 1, 1); G8_STB(G8_SB(1, 0), b3, sg2, 0); G8_STB(G8_SB(1, 1), b3, sg2, 1); G8_STA(G8_SA(1, 0), a3, sg2, 0);
;             G8_WAIT_V(8); G8_WAIT_L(0); G8_BAR; G8_MMA(1, 0, At, B0); G8_MMA(1, 1, At, B1); G8_BAR; G8_SCHED;
;         }
.Lmid_539:
	s_barrier
	s_add_i32 s35, 0, 0x18000
	v_add_u32_e32 v130, s35, v156
	s_add_i32 s20, 0, 0x1c000
	ds_read_b128 v[160:163], v130
	ds_read_b128 v[164:167], v130 offset:1024
	ds_read_b128 v[168:171], v130 offset:2048
	ds_read_b128 v[172:175], v130 offset:3072
	v_add_u32_e32 v130, s20, v156
	ds_read_b128 v[176:179], v130
	ds_read_b128 v[180:183], v130 offset:1024
	ds_read_b128 v[184:187], v130 offset:2048
	ds_read_b128 v[188:191], v130 offset:3072
	s_mov_b32 m0, s15
	v_lshl_add_u64 v[230:231], v[228:229], 0, s[36:37]
	ds_read_b128 v[192:195], v158 offset:32768
	ds_read_b128 v[196:199], v158 offset:33792
	ds_read_b128 v[200:203], v158 offset:34816
	ds_read_b128 v[204:207], v158 offset:35840
	ds_read_b128 v[210:213], v158 offset:36864
	ds_read_b128 v[214:217], v158 offset:37888
	ds_read_b128 v[218:221], v158 offset:38912
	ds_read_b128 v[222:225], v158 offset:39936
	global_load_lds_dwordx4 v[230:231], off
	v_lshl_add_u64 v[230:231], v[228:229], 0, s[38:39]
	s_mov_b32 m0, s16
	s_nop 0
	global_load_lds_dwordx4 v[230:231], off
	s_waitcnt vmcnt(8)
	s_waitcnt lgkmcnt(0)
	s_barrier
	s_waitcnt lgkmcnt(0)
	v_mfma_f32_16x16x32_bf16 v[126:129], v[160:163], v[192:195], v[126:129]
	v_mfma_f32_16x16x32_bf16 v[122:125], v[168:171], v[192:195], v[122:125]
	v_mfma_f32_16x16x32_bf16 v[118:121], v[160:163], v[200:203], v[118:121]
	v_mfma_f32_16x16x32_bf16 v[114:117], v[168:171], v[200:203], v[114:117]
	v_mfma_f32_16x16x32_bf16 v[102:105], v[160:163], v[210:213], v[102:105]
	v_mfma_f32_16x16x32_bf16 v[98:101], v[168:171], v[210:213], v[98:101]
	v_mfma_f32_16x16x32_bf16 v[86:89], v[160:163], v[218:221], v[86:89]
	v_mfma_f32_16x16x32_bf16 v[82:85], v[168:171], v[218:221], v[82:85]
	v_mfma_f32_16x16x32_bf16 v[126:129], v[164:167], v[196:199], v[126:129]
	v_mfma_f32_16x16x32_bf16 v[122:125], v[172:175], v[196:199], v[122:125]
	v_mfma_f32_16x16x32_bf16 v[118:121], v[164:167], v[204:207], v[118:121]
	v_mfma_f32_16x16x32_bf16 v[114:117], v[172:175], v[204:207], v[114:117]
	v_mfma_f32_16x16x32_bf16 v[102:105], v[164:167], v[214:217], v[102:105]
	v_mfma_f32_16x16x32_bf16 v[98:101], v[172:175], v[214:217], v[98:101]
	v_mfma_f32_16x16x32_bf16 v[86:89], v[164:167], v[222:225], v[86:89]
	v_mfma_f32_16x16x32_bf16 v[82:85], v[172:175], v[222:225], v[82:85]
	v_mfma_f32_16x16x32_bf16 v[110:113], v[176:179], v[192:195], v[110:113]
	v_mfma_f32_16x16x32_bf16 v[106:109], v[184:187], v[192:195], v[106:109]
	v_mfma_f32_16x16x32_bf16 v[94:97], v[176:179], v[200:203], v[94:97]
	v_mfma_f32_16x16x32_bf16 v[90:93], v[184:187], v[200:203], v[90:93]
	v_mfma_f32_16x16x32_bf16 v[78:81], v[176:179], v[210:213], v[78:81]
	v_mfma_f32_16x16x32_bf16 v[74:77], v[184:187], v[210:213], v[74:77]
	v_mfma_f32_16x16x32_bf16 v[70:73], v[176:179], v[218:221], v[70:73]
	v_mfma_f32_16x16x32_bf16 v[66:69], v[184:187], v[218:221], v[66:69]
	v_mfma_f32_16x16x32_bf16 v[110:113], v[180:183], v[196:199], v[110:113]
	v_mfma_f32_16x16x32_bf16 v[106:109], v[188:191], v[196:199], v[106:109]
	v_mfma_f32_16x16x32_bf16 v[94:97], v[180:183], v[204:207], v[94:97]
	v_mfma_f32_16x16x32_bf16 v[90:93], v[188:191], v[204:207], v[90:93]
	v_mfma_f32_16x16x32_bf16 v[78:81], v[180:183], v[214:217], v[78:81]
	v_mfma_f32_16x16x32_bf16 v[74:77], v[188:191], v[214:217], v[74:77]
	v_mfma_f32_16x16x32_bf16 v[70:73], v[180:183], v[222:225], v[70:73]
	v_mfma_f32_16x16x32_bf16 v[66:69], v[188:191], v[222:225], v[66:69]
	s_barrier
	s_add_i32 s6, s35, s10
	v_lshl_add_u64 v[230:231], v[226:227], 0, s[40:41]
	s_mov_b32 m0, s6
	ds_read_b128 v[192:195], v158 offset:49152
	ds_read_b128 v[196:199], v158 offset:50176
	ds_read_b128 v[200:203], v158 offset:51200
	ds_read_b128 v[204:207], v158 offset:52224
	ds_read_b128 v[210:213], v158 offset:53248
	ds_read_b128 v[214:217], v158 offset:54272
	ds_read_b128 v[218:221], v158 offset:55296
	ds_read_b128 v[222:225], v158 offset:56320
	global_load_lds_dwordx4 v[230:231], off
	v_lshl_add_u64 v[230:231], v[226:227], 0, s[42:43]
	s_add_i32 m0, s6, 0x2000
	s_add_i32 s6, s20, s10
	global_load_lds_dwordx4 v[230:231], off
	v_lshl_add_u64 v[230:231], v[226:227], 0, s[48:49]
	s_mov_b32 m0, s6
	v_lshl_add_u64 v[226:227], v[226:227], 0, s[52:53]
	global_load_lds_dwordx4 v[230:231], off
	s_add_i32 m0, s6, 0x2000
	s_nop 0
	global_load_lds_dwordx4 v[226:227], off
	v_lshl_add_u64 v[226:227], v[228:229], 0, s[8:9]
	s_mov_b32 m0, s24
	s_nop 0
	global_load_lds_dwordx4 v[226:227], off
	v_lshl_add_u64 v[226:227], v[228:229], 0, s[44:45]
	s_mov_b32 m0, s25
	s_nop 0
	global_load_lds_dwordx4 v[226:227], off
	s_waitcnt vmcnt(8)
	s_waitcnt lgkmcnt(0)
	s_barrier
	s_waitcnt lgkmcnt(0)
	v_mfma_f32_16x16x32_bf16 v[62:65], v[160:163], v[192:195], v[62:65]
	v_mfma_f32_16x16x32_bf16 v[58:61], v[168:171], v[192:195], v[58:61]
	v_mfma_f32_16x16x32_bf16 v[54:57], v[160:163], v[200:203], v[54:57]
	v_mfma_f32_16x16x32_bf16 v[50:53], v[168:171], v[200:203], v[50:53]
	s_add_i32 s47, s47, 2
	v_mfma_f32_16x16x32_bf16 v[38:41], v[160:163], v[210:213], v[38:41]
	s_add_u32 s28, s28, 0x40000
	v_mfma_f32_16x16x32_bf16 v[34:37], v[168:171], v[210:213], v[34:37]
	s_addc_u32 s29, s29, 0
	v_mfma_f32_16x16x32_bf16 v[22:25], v[160:163], v[218:221], v[22:25]
	s_add_u32 s94, s94, 0x10000
	v_mfma_f32_16x16x32_bf16 v[18:21], v[168:171], v[218:221], v[18:21]
	s_addc_u32 s95, s95, 0
	v_mfma_f32_16x16x32_bf16 v[62:65], v[164:167], v[196:199], v[62:65]
	s_cmp_gt_u32 s47, 5
	v_mfma_f32_16x16x32_bf16 v[58:61], v[172:175], v[196:199], v[58:61]
	v_mfma_f32_16x16x32_bf16 v[54:57], v[164:167], v[204:207], v[54:57]
	v_mfma_f32_16x16x32_bf16 v[50:53], v[172:175], v[204:207], v[50:53]
	v_mfma_f32_16x16x32_bf16 v[38:41], v[164:167], v[214:217], v[38:41]
	v_mfma_f32_16x16x32_bf16 v[34:37], v[172:175], v[214:217], v[34:37]
	v_mfma_f32_16x16x32_bf16 v[22:25], v[164:167], v[222:225], v[22:25]
	v_mfma_f32_16x16x32_bf16 v[18:21], v[172:175], v[222:225], v[18:21]
	v_mfma_f32_16x16x32_bf16 v[46:49], v[176:179], v[192:195], v[46:49]
	v_mfma_f32_16x16x32_bf16 v[42:45], v[184:187], v[192:195], v[42:45]
	v_mfma_f32_16x16x32_bf16 v[30:33], v[176:179], v[200:203], v[30:33]
	v_mfma_f32_16x16x32_bf16 v[26:29], v[184:187], v[200:203], v[26:29]
	v_mfma_f32_16x16x32_bf16 v[14:17], v[176:179], v[210:213], v[14:17]
	v_mfma_f32_16x16x32_bf16 v[10:13], v[184:187], v[210:213], v[10:13]
	v_mfma_f32_16x16x32_bf16 v[6:9], v[176:179], v[218:221], v[6:9]
	v_mfma_f32_16x16x32_bf16 v[2:5], v[184:187], v[218:221], v[2:5]
	v_mfma_f32_16x16x32_bf16 v[46:49], v[180:183], v[196:199], v[46:49]
	v_mfma_f32_16x16x32_bf16 v[42:45], v[188:191], v[196:199], v[42:45]
	v_mfma_f32_16x16x32_bf16 v[30:33], v[180:183], v[204:207], v[30:33]
	v_mfma_f32_16x16x32_bf16 v[26:29], v[188:191], v[204:207], v[26:29]
	v_mfma_f32_16x16x32_bf16 v[14:17], v[180:183], v[214:217], v[14:17]
	v_mfma_f32_16x16x32_bf16 v[10:13], v[188:191], v[214:217], v[10:13]
	v_mfma_f32_16x16x32_bf16 v[6:9], v[180:183], v[222:225], v[6:9]
	v_mfma_f32_16x16x32_bf16 v[2:5], v[188:191], v[222:225], v[2:5]
	s_barrier
	s_cbranch_scc0 .LBB0_539
	s_and_b64 vcc, exec, s[86:87]
	s_cbranch_vccz .LBB0_542
	s_barrier

; #define G8_STA(bufoff, ptr, sg, h) G8_STAGE1(bufoff, (ptr) + (h) * ((sg) ? hA1 : hA0), ((sg) ? voffA1 : voffA0), ((sg) ? r64A1 : r64A0))
; #define G8_STB(bufoff, ptr, sg, h) G8_STAGE1(bufoff, (ptr) + (h) * ((sg) ? hB1 : hB0), ((sg) ? voffB1 : voffB0), ((sg) ? r64B1 : r64B0))
; #define G8_LDA(dst, b, h) do { _Pragma("unroll") for (int m = 0; m < 4; ++m) _Pragma("unroll") for (int k = 0; k < 2; ++k) dst[m][k] = *(const LAS bf16x8*)(lds + G8_SA(b, h) + aoff + m * 2048 + k * 1024); } while (0)
; #define G8_LDB(dst, b, h) do { _Pragma("unroll") for (int n = 0; n < 2; ++n) _Pragma("unroll") for (int k = 0; k < 2; ++k) dst[n][k] = *(const LAS bf16x8*)(lds + G8_SB(b, h) + boff + n * 2048 + k * 1024); } while (0)
; #define G8_MMA(ai, bj, At, Bt) do { __builtin_amdgcn_s_setprio(1); _Pragma("unroll") for (int m = 0; m < 4; ++m) _Pragma("unroll") for (int n = 0; n < 2; ++n) _Pragma("unroll") for (int k = 0; k < 2; ++k) \
;         acc[ai][bj][m][n] = __builtin_amdgcn_mfma_f32_16x16x32_bf16(Bt[n][k], At[m][k], acc[ai][bj][m][n], 0, 0, 0); __builtin_amdgcn_s_setprio(0); } while (0)
; #define G8_WAIT_V(n) asm volatile("s_waitcnt vmcnt(" #n ")" ::: "memory")
; #define G8_WAIT_L(n) asm volatile("s_waitcnt lgkmcnt(" #n ")" ::: "memory")
; #define G8_BAR __builtin_amdgcn_s_barrier()
; #define G8_SCHED __builtin_amdgcn_sched_barrier(0)
; template <class P>
; __device__ __forceinline__ void gemm_phase(LAS unsigned char* lds, const P& p, const int G, const int c) {
;     ...
;             G8_LDB(B0, 1, 0); G8_LDB(B1, 1, 1); G8_SCHED; G8_LDA(At, 1, 0); G8_STA(G8_SA(0, 1), a2, sg2, 1);
;             G8_WAIT_V(8); G8_WAIT_L(0); G8_BAR; G8_MMA(0, 0, At, B0); G8_MMA(0, 1, At, B1); G8_BAR; G8_SCHED;
;             G8_LDA(At, 1, 1); G8_STB(G8_SB(1, 0), b3, sg2, 0); G8_STB(G8_SB(1, 1), b3, sg2, 1); G8_STA(G8_SA(1, 0), a3, sg2, 0);
;             G8_WAIT_V(8); G8_WAIT_L(0); G8_BAR; G8_MMA(1, 0, At, B0); G8_MMA(1, 1, At, B1); G8_BAR; G8_SCHED;
;         }
.Lmid_679:
	s_barrier
	s_add_i32 s28, 0, 0x18000
	v_add_u32_e32 v153, s28, v1
	s_add_i32 s29, 0, 0x1c000
	ds_read_b128 v[170:173], v153
	ds_read_b128 v[174:177], v153 offset:1024
	ds_read_b128 v[178:181], v153 offset:2048
	ds_read_b128 v[182:185], v153 offset:3072
	v_add_u32_e32 v153, s29, v1
	ds_read_b128 v[186:189], v153
	ds_read_b128 v[190:193], v153 offset:1024
	ds_read_b128 v[194:197], v153 offset:2048
	ds_read_b128 v[198:201], v153 offset:3072
	s_mov_b32 m0, s34
	v_lshl_add_u64 v[240:241], v[238:239], 0, s[4:5]
	ds_read_b128 v[202:205], v151 offset:32768
	ds_read_b128 v[210:213], v151 offset:33792
	ds_read_b128 v[214:217], v151 offset:34816
	ds_read_b128 v[218:221], v151 offset:35840
	ds_read_b128 v[222:225], v151 offset:36864
	ds_read_b128 v[226:229], v151 offset:37888
	ds_read_b128 v[230:233], v151 offset:38912
	ds_read_b128 v[234:237], v151 offset:39936
	global_load_lds_dwordx4 v[240:241], off
	v_lshl_add_u64 v[240:241], v[238:239], 0, s[6:7]
	s_mov_b32 m0, s35
	s_nop 0
	global_load_lds_dwordx4 v[240:241], off
	s_waitcnt vmcnt(8)
	s_waitcnt lgkmcnt(0)
	s_barrier
	s_waitcnt lgkmcnt(0)
	v_mfma_f32_16x16x32_bf16 v[126:129], v[170:173], v[202:205], v[126:129]
	v_mfma_f32_16x16x32_bf16 v[122:125], v[178:181], v[202:205], v[122:125]
	v_mfma_f32_16x16x32_bf16 v[110:113], v[170:173], v[214:217], v[110:113]
	v_mfma_f32_16x16x32_bf16 v[106:109], v[178:181], v[214:217], v[106:109]
	v_mfma_f32_16x16x32_bf16 v[94:97], v[170:173], v[222:225], v[94:97]
	v_mfma_f32_16x16x32_bf16 v[90:93], v[178:181], v[222:225], v[90:93]
	v_mfma_f32_16x16x32_bf16 v[78:81], v[170:173], v[230:233], v[78:81]
	v_mfma_f32_16x16x32_bf16 v[74:77], v[178:181], v[230:233], v[74:77]
	v_mfma_f32_16x16x32_bf16 v[126:129], v[174:177], v[210:213], v[126:129]
	v_mfma_f32_16x16x32_bf16 v[122:125], v[182:185], v[210:213], v[122:125]
	v_mfma_f32_16x16x32_bf16 v[110:113], v[174:177], v[218:221], v[110:113]
	v_mfma_f32_16x16x32_bf16 v[106:109], v[182:185], v[218:221], v[106:109]
	v_mfma_f32_16x16x32_bf16 v[94:97], v[174:177], v[226:229], v[94:97]
	v_mfma_f32_16x16x32_bf16 v[90:93], v[182:185], v[226:229], v[90:93]
	v_mfma_f32_16x16x32_bf16 v[78:81], v[174:177], v[234:237], v[78:81]
	v_mfma_f32_16x16x32_bf16 v[74:77], v[182:185], v[234:237], v[74:77]
	v_mfma_f32_16x16x32_bf16 v[118:121], v[186:189], v[202:205], v[118:121]
	v_mfma_f32_16x16x32_bf16 v[114:117], v[194:197], v[202:205], v[114:117]
	v_mfma_f32_16x16x32_bf16 v[102:105], v[186:189], v[214:217], v[102:105]
	v_mfma_f32_16x16x32_bf16 v[98:101], v[194:197], v[214:217], v[98:101]
	v_mfma_f32_16x16x32_bf16 v[86:89], v[186:189], v[222:225], v[86:89]
	v_mfma_f32_16x16x32_bf16 v[82:85], v[194:197], v[222:225], v[82:85]
	v_mfma_f32_16x16x32_bf16 v[70:73], v[186:189], v[230:233], v[70:73]
	v_mfma_f32_16x16x32_bf16 v[66:69], v[194:197], v[230:233], v[66:69]
	v_mfma_f32_16x16x32_bf16 v[118:121], v[190:193], v[210:213], v[118:121]
	v_mfma_f32_16x16x32_bf16 v[114:117], v[198:201], v[210:213], v[114:117]
	v_mfma_f32_16x16x32_bf16 v[102:105], v[190:193], v[218:221], v[102:105]
	v_mfma_f32_16x16x32_bf16 v[98:101], v[198:201], v[218:221], v[98:101]
	v_mfma_f32_16x16x32_bf16 v[86:89], v[190:193], v[226:229], v[86:89]
	v_mfma_f32_16x16x32_bf16 v[82:85], v[198:201], v[226:229], v[82:85]
	v_mfma_f32_16x16x32_bf16 v[70:73], v[190:193], v[234:237], v[70:73]
	v_mfma_f32_16x16x32_bf16 v[66:69], v[198:201], v[234:237], v[66:69]
	s_barrier
	s_add_i32 s28, s28, s26
	v_lshl_add_u64 v[240:241], v[206:207], 0, s[12:13]
	s_mov_b32 m0, s28
	ds_read_b128 v[202:205], v151 offset:49152
	ds_read_b128 v[210:213], v151 offset:50176
	ds_read_b128 v[214:217], v151 offset:51200
	ds_read_b128 v[218:221], v151 offset:52224
	ds_read_b128 v[222:225], v151 offset:53248
	ds_read_b128 v[226:229], v151 offset:54272
	ds_read_b128 v[230:233], v151 offset:55296
	ds_read_b128 v[234:237], v151 offset:56320
	global_load_lds_dwordx4 v[240:241], off
	v_lshl_add_u64 v[240:241], v[206:207], 0, s[14:15]
	s_add_i32 m0, s28, 0x2000
	s_add_i32 s28, s29, s26
	global_load_lds_dwordx4 v[240:241], off
	v_lshl_add_u64 v[240:241], v[206:207], 0, s[22:23]
	s_mov_b32 m0, s28
	v_lshl_add_u64 v[206:207], v[206:207], 0, s[36:37]
	global_load_lds_dwordx4 v[240:241], off
	s_add_i32 m0, s28, 0x2000
	s_nop 0
	global_load_lds_dwordx4 v[206:207], off
	v_lshl_add_u64 v[206:207], v[238:239], 0, s[16:17]
	s_mov_b32 m0, s46
	s_nop 0
	global_load_lds_dwordx4 v[206:207], off
	v_lshl_add_u64 v[206:207], v[238:239], 0, s[20:21]
	s_mov_b32 m0, s47
	s_nop 0
	global_load_lds_dwordx4 v[206:207], off
	s_waitcnt vmcnt(8)
	s_waitcnt lgkmcnt(0)
	s_barrier
	s_waitcnt lgkmcnt(0)
	v_mfma_f32_16x16x32_bf16 v[62:65], v[170:173], v[202:205], v[62:65]
	v_mfma_f32_16x16x32_bf16 v[58:61], v[178:181], v[202:205], v[58:61]
	v_mfma_f32_16x16x32_bf16 v[46:49], v[170:173], v[214:217], v[46:49]
	v_mfma_f32_16x16x32_bf16 v[42:45], v[178:181], v[214:217], v[42:45]
	s_add_i32 s66, s66, 2
	v_mfma_f32_16x16x32_bf16 v[30:33], v[170:173], v[222:225], v[30:33]
	s_add_u32 s53, s53, 0x100000
	v_mfma_f32_16x16x32_bf16 v[26:29], v[178:181], v[222:225], v[26:29]
	s_addc_u32 s59, s59, 0
	v_mfma_f32_16x16x32_bf16 v[14:17], v[170:173], v[230:233], v[14:17]
	s_add_u32 s62, s62, 0x820000
	v_mfma_f32_16x16x32_bf16 v[10:13], v[178:181], v[230:233], v[10:13]
	s_addc_u32 s63, s63, 0
	v_mfma_f32_16x16x32_bf16 v[62:65], v[174:177], v[210:213], v[62:65]
	s_cmp_gt_u32 s66, 13
	v_mfma_f32_16x16x32_bf16 v[58:61], v[182:185], v[210:213], v[58:61]
	v_mfma_f32_16x16x32_bf16 v[46:49], v[174:177], v[218:221], v[46:49]
	v_mfma_f32_16x16x32_bf16 v[42:45], v[182:185], v[218:221], v[42:45]
	v_mfma_f32_16x16x32_bf16 v[30:33], v[174:177], v[226:229], v[30:33]
	v_mfma_f32_16x16x32_bf16 v[26:29], v[182:185], v[226:229], v[26:29]
	v_mfma_f32_16x16x32_bf16 v[14:17], v[174:177], v[234:237], v[14:17]
	v_mfma_f32_16x16x32_bf16 v[10:13], v[182:185], v[234:237], v[10:13]
	v_mfma_f32_16x16x32_bf16 v[54:57], v[186:189], v[202:205], v[54:57]
	v_mfma_f32_16x16x32_bf16 v[50:53], v[194:197], v[202:205], v[50:53]
	v_mfma_f32_16x16x32_bf16 v[38:41], v[186:189], v[214:217], v[38:41]
	v_mfma_f32_16x16x32_bf16 v[34:37], v[194:197], v[214:217], v[34:37]
	v_mfma_f32_16x16x32_bf16 v[22:25], v[186:189], v[222:225], v[22:25]
	v_mfma_f32_16x16x32_bf16 v[18:21], v[194:197], v[222:225], v[18:21]
	v_mfma_f32_16x16x32_bf16 v[6:9], v[186:189], v[230:233], v[6:9]
	v_mfma_f32_16x16x32_bf16 v[2:5], v[194:197], v[230:233], v[2:5]
	v_mfma_f32_16x16x32_bf16 v[54:57], v[190:193], v[210:213], v[54:57]
	v_mfma_f32_16x16x32_bf16 v[50:53], v[198:201], v[210:213], v[50:53]
	v_mfma_f32_16x16x32_bf16 v[38:41], v[190:193], v[218:221], v[38:41]
	v_mfma_f32_16x16x32_bf16 v[34:37], v[198:201], v[218:221], v[34:37]
	v_mfma_f32_16x16x32_bf16 v[22:25], v[190:193], v[226:229], v[22:25]
	v_mfma_f32_16x16x32_bf16 v[18:21], v[198:201], v[226:229], v[18:21]
	v_mfma_f32_16x16x32_bf16 v[6:9], v[190:193], v[234:237], v[6:9]
	v_mfma_f32_16x16x32_bf16 v[2:5], v[198:201], v[234:237], v[2:5]
	s_barrier
	s_cbranch_scc1 .LBB0_682

; #define G8_STA(bufoff, ptr, sg, h) G8_STAGE1(bufoff, (ptr) + (h) * ((sg) ? hA1 : hA0), ((sg) ? voffA1 : voffA0), ((sg) ? r64A1 : r64A0))
; #define G8_STB(bufoff, ptr, sg, h) G8_STAGE1(bufoff, (ptr) + (h) * ((sg) ? hB1 : hB0), ((sg) ? voffB1 : voffB0), ((sg) ? r64B1 : r64B0))
; #define G8_LDA(dst, b, h) do { _Pragma("unroll") for (int m = 0; m < 4; ++m) _Pragma("unroll") for (int k = 0; k < 2; ++k) dst[m][k] = *(const LAS bf16x8*)(lds + G8_SA(b, h) + aoff + m * 2048 + k * 1024); } while (0)
; #define G8_LDB(dst, b, h) do { _Pragma("unroll") for (int n = 0; n < 2; ++n) _Pragma("unroll") for (int k = 0; k < 2; ++k) dst[n][k] = *(const LAS bf16x8*)(lds + G8_SB(b, h) + boff + n * 2048 + k * 1024); } while (0)
; #define G8_MMA(ai, bj, At, Bt) do { __builtin_amdgcn_s_setprio(1); _Pragma("unroll") for (int m = 0; m < 4; ++m) _Pragma("unroll") for (int n = 0; n < 2; ++n) _Pragma("unroll") for (int k = 0; k < 2; ++k) \
;         acc[ai][bj][m][n] = __builtin_amdgcn_mfma_f32_16x16x32_bf16(Bt[n][k], At[m][k], acc[ai][bj][m][n], 0, 0, 0); __builtin_amdgcn_s_setprio(0); } while (0)
; #define G8_WAIT_V(n) asm volatile("s_waitcnt vmcnt(" #n ")" ::: "memory")
; #define G8_WAIT_L(n) asm volatile("s_waitcnt lgkmcnt(" #n ")" ::: "memory")
; #define G8_BAR __builtin_amdgcn_s_barrier()
; #define G8_SCHED __builtin_amdgcn_sched_barrier(0)
; template <class P>
; __device__ __forceinline__ void gemm_phase(LAS unsigned char* lds, const P& p, const int G, const int c) {
;     ...
;             G8_LDB(B0, 1, 0); G8_LDB(B1, 1, 1); G8_SCHED; G8_LDA(At, 1, 0); G8_STA(G8_SA(0, 1), a2, sg2, 1);
;             G8_WAIT_V(8); G8_WAIT_L(0); G8_BAR; G8_MMA(0, 0, At, B0); G8_MMA(0, 1, At, B1); G8_BAR; G8_SCHED;
;             G8_LDA(At, 1, 1); G8_STB(G8_SB(1, 0), b3, sg2, 0); G8_STB(G8_SB(1, 1), b3, sg2, 1); G8_STA(G8_SA(1, 0), a3, sg2, 0);
;             G8_WAIT_V(8); G8_WAIT_L(0); G8_BAR; G8_MMA(1, 0, At, B0); G8_MMA(1, 1, At, B1); G8_BAR; G8_SCHED;
;         }
.Lmid_707:
	s_barrier
	s_add_i32 s65, 0, 0x18000
	v_add_u32_e32 v84, s65, v229
	s_add_i32 s66, 0, 0x1c000
	ds_read_b128 v[68:71], v84
	ds_read_b128 v[72:75], v84 offset:1024
	ds_read_b128 v[76:79], v84 offset:2048
	ds_read_b128 v[138:141], v84 offset:3072
	v_add_u32_e32 v84, s66, v229
	ds_read_b128 v[142:145], v84
	ds_read_b128 v[154:157], v84 offset:1024
	ds_read_b128 v[158:161], v84 offset:2048
	ds_read_b128 v[162:165], v84 offset:3072
	s_mov_b32 m0, s27
	v_lshl_add_u64 v[84:85], v[200:201], 0, s[14:15]
	ds_read_b128 v[166:169], v232 offset:32768
	ds_read_b128 v[170:173], v232 offset:33792
	ds_read_b128 v[174:177], v232 offset:34816
	ds_read_b128 v[178:181], v232 offset:35840
	ds_read_b128 v[182:185], v232 offset:36864
	ds_read_b128 v[186:189], v232 offset:37888
	ds_read_b128 v[190:193], v232 offset:38912
	ds_read_b128 v[194:197], v232 offset:39936
	global_load_lds_dwordx4 v[84:85], off
	v_lshl_add_u64 v[84:85], v[200:201], 0, s[16:17]
	s_mov_b32 m0, s31
	s_nop 0
	global_load_lds_dwordx4 v[84:85], off
	s_waitcnt vmcnt(8)
	s_waitcnt lgkmcnt(0)
	s_barrier
	s_waitcnt lgkmcnt(0)
	v_mfma_f32_16x16x32_bf16 v[150:153], v[68:71], v[166:169], v[150:153]
	v_mfma_f32_16x16x32_bf16 v[146:149], v[76:79], v[166:169], v[146:149]
	v_mfma_f32_16x16x32_bf16 v[126:129], v[68:71], v[174:177], v[126:129]
	v_mfma_f32_16x16x32_bf16 v[122:125], v[76:79], v[174:177], v[122:125]
	v_mfma_f32_16x16x32_bf16 v[110:113], v[68:71], v[182:185], v[110:113]
	v_mfma_f32_16x16x32_bf16 v[106:109], v[76:79], v[182:185], v[106:109]
	v_mfma_f32_16x16x32_bf16 v[94:97], v[68:71], v[190:193], v[94:97]
	v_mfma_f32_16x16x32_bf16 v[90:93], v[76:79], v[190:193], v[90:93]
	v_mfma_f32_16x16x32_bf16 v[150:153], v[72:75], v[170:173], v[150:153]
	v_mfma_f32_16x16x32_bf16 v[146:149], v[138:141], v[170:173], v[146:149]
	v_mfma_f32_16x16x32_bf16 v[126:129], v[72:75], v[178:181], v[126:129]
	v_mfma_f32_16x16x32_bf16 v[122:125], v[138:141], v[178:181], v[122:125]
	v_mfma_f32_16x16x32_bf16 v[110:113], v[72:75], v[186:189], v[110:113]
	v_mfma_f32_16x16x32_bf16 v[106:109], v[138:141], v[186:189], v[106:109]
	v_mfma_f32_16x16x32_bf16 v[94:97], v[72:75], v[194:197], v[94:97]
	v_mfma_f32_16x16x32_bf16 v[90:93], v[138:141], v[194:197], v[90:93]
	v_mfma_f32_16x16x32_bf16 v[134:137], v[142:145], v[166:169], v[134:137]
	v_mfma_f32_16x16x32_bf16 v[130:133], v[158:161], v[166:169], v[130:133]
	v_mfma_f32_16x16x32_bf16 v[118:121], v[142:145], v[174:177], v[118:121]
	v_mfma_f32_16x16x32_bf16 v[114:117], v[158:161], v[174:177], v[114:117]
	v_mfma_f32_16x16x32_bf16 v[102:105], v[142:145], v[182:185], v[102:105]
	v_mfma_f32_16x16x32_bf16 v[98:101], v[158:161], v[182:185], v[98:101]
	v_mfma_f32_16x16x32_bf16 v[84:87], v[142:145], v[190:193], v[86:89]
	v_mfma_f32_16x16x32_bf16 v[80:83], v[158:161], v[190:193], v[80:83]
	v_mfma_f32_16x16x32_bf16 v[134:137], v[154:157], v[170:173], v[134:137]
	v_mfma_f32_16x16x32_bf16 v[130:133], v[162:165], v[170:173], v[130:133]
	v_mfma_f32_16x16x32_bf16 v[118:121], v[154:157], v[178:181], v[118:121]
	v_mfma_f32_16x16x32_bf16 v[114:117], v[162:165], v[178:181], v[114:117]
	v_mfma_f32_16x16x32_bf16 v[102:105], v[154:157], v[186:189], v[102:105]
	v_mfma_f32_16x16x32_bf16 v[98:101], v[162:165], v[186:189], v[98:101]
	v_mfma_f32_16x16x32_bf16 v[86:89], v[154:157], v[194:197], v[84:87]
	v_mfma_f32_16x16x32_bf16 v[82:85], v[162:165], v[194:197], v[80:83]
	s_barrier
	s_add_i32 s65, s65, s24
	v_lshl_add_u64 v[80:81], v[198:199], 0, s[36:37]
	s_mov_b32 m0, s65
	ds_read_b128 v[166:169], v232 offset:49152
	ds_read_b128 v[170:173], v232 offset:50176
	ds_read_b128 v[174:177], v232 offset:51200
	ds_read_b128 v[178:181], v232 offset:52224
	ds_read_b128 v[182:185], v232 offset:53248
	ds_read_b128 v[186:189], v232 offset:54272
	ds_read_b128 v[190:193], v232 offset:55296
	ds_read_b128 v[194:197], v232 offset:56320
	global_load_lds_dwordx4 v[80:81], off
	v_lshl_add_u64 v[80:81], v[198:199], 0, s[38:39]
	s_add_i32 m0, s65, 0x2000
	s_add_i32 s65, s66, s24
	global_load_lds_dwordx4 v[80:81], off
	v_lshl_add_u64 v[80:81], v[198:199], 0, s[44:45]
	s_mov_b32 m0, s65
	s_nop 0
	global_load_lds_dwordx4 v[80:81], off
	v_lshl_add_u64 v[80:81], v[198:199], 0, s[48:49]
	s_add_i32 m0, s65, 0x2000
	s_nop 0
	global_load_lds_dwordx4 v[80:81], off
	v_lshl_add_u64 v[80:81], v[200:201], 0, s[40:41]
	s_mov_b32 m0, s46
	s_nop 0
	global_load_lds_dwordx4 v[80:81], off
	v_lshl_add_u64 v[80:81], v[200:201], 0, s[42:43]
	s_mov_b32 m0, s47
	s_nop 0
	global_load_lds_dwordx4 v[80:81], off
	s_waitcnt vmcnt(8)
	s_waitcnt lgkmcnt(0)
	s_barrier
	s_waitcnt lgkmcnt(0)
	v_mfma_f32_16x16x32_bf16 v[62:65], v[68:71], v[166:169], v[62:65]
	v_mfma_f32_16x16x32_bf16 v[58:61], v[76:79], v[166:169], v[58:61]
	v_mfma_f32_16x16x32_bf16 v[46:49], v[68:71], v[174:177], v[46:49]
	v_mfma_f32_16x16x32_bf16 v[42:45], v[76:79], v[174:177], v[42:45]
	s_add_i32 s64, s64, 2
	v_mfma_f32_16x16x32_bf16 v[30:33], v[68:71], v[182:185], v[30:33]
	s_add_u32 s28, s28, 0x80000
	v_mfma_f32_16x16x32_bf16 v[26:29], v[76:79], v[182:185], v[26:29]
	s_addc_u32 s29, s29, 0
	v_mfma_f32_16x16x32_bf16 v[14:17], v[68:71], v[190:193], v[14:17]
	s_add_u32 s76, s76, 0x800000
	v_mfma_f32_16x16x32_bf16 v[10:13], v[76:79], v[190:193], v[10:13]
	s_addc_u32 s77, s77, 0
	v_mfma_f32_16x16x32_bf16 v[62:65], v[72:75], v[170:173], v[62:65]
	s_cmp_gt_u32 s64, 29
	v_mfma_f32_16x16x32_bf16 v[58:61], v[138:141], v[170:173], v[58:61]
	v_mfma_f32_16x16x32_bf16 v[46:49], v[72:75], v[178:181], v[46:49]
	v_mfma_f32_16x16x32_bf16 v[42:45], v[138:141], v[178:181], v[42:45]
	v_mfma_f32_16x16x32_bf16 v[30:33], v[72:75], v[186:189], v[30:33]
	v_mfma_f32_16x16x32_bf16 v[26:29], v[138:141], v[186:189], v[26:29]
	v_mfma_f32_16x16x32_bf16 v[14:17], v[72:75], v[194:197], v[14:17]
	v_mfma_f32_16x16x32_bf16 v[10:13], v[138:141], v[194:197], v[10:13]
	v_mfma_f32_16x16x32_bf16 v[54:57], v[142:145], v[166:169], v[54:57]
	v_mfma_f32_16x16x32_bf16 v[50:53], v[158:161], v[166:169], v[50:53]
	v_mfma_f32_16x16x32_bf16 v[38:41], v[142:145], v[174:177], v[38:41]
	v_mfma_f32_16x16x32_bf16 v[34:37], v[158:161], v[174:177], v[34:37]
	v_mfma_f32_16x16x32_bf16 v[22:25], v[142:145], v[182:185], v[22:25]
	v_mfma_f32_16x16x32_bf16 v[18:21], v[158:161], v[182:185], v[18:21]
	v_mfma_f32_16x16x32_bf16 v[6:9], v[142:145], v[190:193], v[6:9]
	v_mfma_f32_16x16x32_bf16 v[2:5], v[158:161], v[190:193], v[2:5]
	v_mfma_f32_16x16x32_bf16 v[54:57], v[154:157], v[170:173], v[54:57]
	v_mfma_f32_16x16x32_bf16 v[50:53], v[162:165], v[170:173], v[50:53]
	v_mfma_f32_16x16x32_bf16 v[38:41], v[154:157], v[178:181], v[38:41]
	v_mfma_f32_16x16x32_bf16 v[34:37], v[162:165], v[178:181], v[34:37]
	v_mfma_f32_16x16x32_bf16 v[22:25], v[154:157], v[186:189], v[22:25]
	v_mfma_f32_16x16x32_bf16 v[18:21], v[162:165], v[186:189], v[18:21]
	v_mfma_f32_16x16x32_bf16 v[6:9], v[154:157], v[194:197], v[6:9]
	v_mfma_f32_16x16x32_bf16 v[2:5], v[162:165], v[194:197], v[2:5]
	s_barrier
	s_cbranch_scc0 .LBB0_707
	s_and_b64 vcc, exec, s[52:53]
	s_cbranch_vccz .LBB0_710
	s_barrier

; #define G8_STA(bufoff, ptr, sg, h) G8_STAGE1(bufoff, (ptr) + (h) * ((sg) ? hA1 : hA0), ((sg) ? voffA1 : voffA0), ((sg) ? r64A1 : r64A0))
; #define G8_STB(bufoff, ptr, sg, h) G8_STAGE1(bufoff, (ptr) + (h) * ((sg) ? hB1 : hB0), ((sg) ? voffB1 : voffB0), ((sg) ? r64B1 : r64B0))
; #define G8_LDA(dst, b, h) do { _Pragma("unroll") for (int m = 0; m < 4; ++m) _Pragma("unroll") for (int k = 0; k < 2; ++k) dst[m][k] = *(const LAS bf16x8*)(lds + G8_SA(b, h) + aoff + m * 2048 + k * 1024); } while (0)
; #define G8_LDB(dst, b, h) do { _Pragma("unroll") for (int n = 0; n < 2; ++n) _Pragma("unroll") for (int k = 0; k < 2; ++k) dst[n][k] = *(const LAS bf16x8*)(lds + G8_SB(b, h) + boff + n * 2048 + k * 1024); } while (0)
; #define G8_MMA(ai, bj, At, Bt) do { __builtin_amdgcn_s_setprio(1); _Pragma("unroll") for (int m = 0; m < 4; ++m) _Pragma("unroll") for (int n = 0; n < 2; ++n) _Pragma("unroll") for (int k = 0; k < 2; ++k) \
;         acc[ai][bj][m][n] = __builtin_amdgcn_mfma_f32_16x16x32_bf16(Bt[n][k], At[m][k], acc[ai][bj][m][n], 0, 0, 0); __builtin_amdgcn_s_setprio(0); } while (0)
; #define G8_WAIT_V(n) asm volatile("s_waitcnt vmcnt(" #n ")" ::: "memory")
; #define G8_WAIT_L(n) asm volatile("s_waitcnt lgkmcnt(" #n ")" ::: "memory")
; #define G8_BAR __builtin_amdgcn_s_barrier()
; #define G8_SCHED __builtin_amdgcn_sched_barrier(0)
; template <class P>
; __device__ __forceinline__ void gemm_phase(LAS unsigned char* lds, const P& p, const int G, const int c) {
;     ...
;             G8_LDB(B0, 1, 0); G8_LDB(B1, 1, 1); G8_SCHED; G8_LDA(At, 1, 0); G8_STA(G8_SA(0, 1), a2, sg2, 1);
;             G8_WAIT_V(8); G8_WAIT_L(0); G8_BAR; G8_MMA(0, 0, At, B0); G8_MMA(0, 1, At, B1); G8_BAR; G8_SCHED;
;             G8_LDA(At, 1, 1); G8_STB(G8_SB(1, 0), b3, sg2, 0); G8_STB(G8_SB(1, 1), b3, sg2, 1); G8_STA(G8_SA(1, 0), a3, sg2, 0);
;             G8_WAIT_V(8); G8_WAIT_L(0); G8_BAR; G8_MMA(1, 0, At, B0); G8_MMA(1, 1, At, B1); G8_BAR; G8_SCHED;
;         }
.Lmid_770:
	s_barrier
	s_add_i32 s77, 0, 0x18000
	v_add_u32_e32 v161, s77, v156
	s_add_i32 s78, 0, 0x1c000
	ds_read_b128 v[130:133], v161
	ds_read_b128 v[134:137], v161 offset:1024
	ds_read_b128 v[138:141], v161 offset:2048
	ds_read_b128 v[162:165], v161 offset:3072
	v_add_u32_e32 v161, s78, v156
	ds_read_b128 v[166:169], v161
	ds_read_b128 v[170:173], v161 offset:1024
	ds_read_b128 v[174:177], v161 offset:2048
	ds_read_b128 v[178:181], v161 offset:3072
	s_mov_b32 m0, s33
	v_lshl_add_u64 v[206:207], v[154:155], 0, s[6:7]
	ds_read_b128 v[182:185], v160 offset:32768
	ds_read_b128 v[186:189], v160 offset:33792
	ds_read_b128 v[190:193], v160 offset:34816
	ds_read_b128 v[194:197], v160 offset:35840
	ds_read_b128 v[198:201], v160 offset:36864
	ds_read_b128 v[202:205], v160 offset:37888
	ds_read_b128 v[210:213], v160 offset:38912
	ds_read_b128 v[214:217], v160 offset:39936
	global_load_lds_dwordx4 v[206:207], off
	v_lshl_add_u64 v[206:207], v[154:155], 0, s[8:9]
	s_mov_b32 m0, s34
	s_nop 0
	global_load_lds_dwordx4 v[206:207], off
	s_waitcnt vmcnt(8)
	s_waitcnt lgkmcnt(0)
	s_barrier
	s_waitcnt lgkmcnt(0)
	v_mfma_f32_16x16x32_bf16 v[120:123], v[130:133], v[182:185], v[120:123]
	v_mfma_f32_16x16x32_bf16 v[124:127], v[138:141], v[182:185], v[124:127]
	v_mfma_f32_16x16x32_bf16 v[112:115], v[130:133], v[190:193], v[112:115]
	v_mfma_f32_16x16x32_bf16 v[116:119], v[138:141], v[190:193], v[116:119]
	v_mfma_f32_16x16x32_bf16 v[100:103], v[130:133], v[198:201], v[100:103]
	v_mfma_f32_16x16x32_bf16 v[108:111], v[138:141], v[198:201], v[108:111]
	v_mfma_f32_16x16x32_bf16 v[84:87], v[130:133], v[210:213], v[84:87]
	v_mfma_f32_16x16x32_bf16 v[72:75], v[138:141], v[210:213], v[72:75]
	v_mfma_f32_16x16x32_bf16 v[120:123], v[134:137], v[186:189], v[120:123]
	v_mfma_f32_16x16x32_bf16 v[124:127], v[162:165], v[186:189], v[124:127]
	v_mfma_f32_16x16x32_bf16 v[112:115], v[134:137], v[194:197], v[112:115]
	v_mfma_f32_16x16x32_bf16 v[116:119], v[162:165], v[194:197], v[116:119]
	v_mfma_f32_16x16x32_bf16 v[100:103], v[134:137], v[202:205], v[100:103]
	v_mfma_f32_16x16x32_bf16 v[108:111], v[162:165], v[202:205], v[108:111]
	v_mfma_f32_16x16x32_bf16 v[84:87], v[134:137], v[214:217], v[84:87]
	v_mfma_f32_16x16x32_bf16 v[72:75], v[162:165], v[214:217], v[72:75]
	v_mfma_f32_16x16x32_bf16 v[104:107], v[166:169], v[182:185], v[104:107]
	v_mfma_f32_16x16x32_bf16 v[92:95], v[174:177], v[182:185], v[92:95]
	v_mfma_f32_16x16x32_bf16 v[96:99], v[166:169], v[190:193], v[96:99]
	v_mfma_f32_16x16x32_bf16 v[80:83], v[174:177], v[190:193], v[80:83]
	v_mfma_f32_16x16x32_bf16 v[88:91], v[166:169], v[198:201], v[88:91]
	v_mfma_f32_16x16x32_bf16 v[76:79], v[174:177], v[198:201], v[76:79]
	v_mfma_f32_16x16x32_bf16 v[68:71], v[166:169], v[210:213], v[68:71]
	v_mfma_f32_16x16x32_bf16 v[64:67], v[174:177], v[210:213], v[64:67]
	v_mfma_f32_16x16x32_bf16 v[104:107], v[170:173], v[186:189], v[104:107]
	v_mfma_f32_16x16x32_bf16 v[92:95], v[178:181], v[186:189], v[92:95]
	v_mfma_f32_16x16x32_bf16 v[96:99], v[170:173], v[194:197], v[96:99]
	v_mfma_f32_16x16x32_bf16 v[80:83], v[178:181], v[194:197], v[80:83]
	v_mfma_f32_16x16x32_bf16 v[88:91], v[170:173], v[202:205], v[88:91]
	v_mfma_f32_16x16x32_bf16 v[76:79], v[178:181], v[202:205], v[76:79]
	v_mfma_f32_16x16x32_bf16 v[68:71], v[170:173], v[214:217], v[68:71]
	v_mfma_f32_16x16x32_bf16 v[64:67], v[178:181], v[214:217], v[64:67]
	s_barrier
	s_add_i32 s77, s77, s26
	v_lshl_add_u64 v[206:207], v[142:143], 0, s[12:13]
	s_mov_b32 m0, s77
	ds_read_b128 v[182:185], v160 offset:49152
	ds_read_b128 v[186:189], v160 offset:50176
	ds_read_b128 v[190:193], v160 offset:51200
	ds_read_b128 v[194:197], v160 offset:52224
	ds_read_b128 v[198:201], v160 offset:53248
	ds_read_b128 v[202:205], v160 offset:54272
	ds_read_b128 v[210:213], v160 offset:55296
	ds_read_b128 v[214:217], v160 offset:56320
	global_load_lds_dwordx4 v[206:207], off
	v_lshl_add_u64 v[206:207], v[142:143], 0, s[14:15]
	s_add_i32 m0, s77, 0x2000
	s_add_i32 s77, s78, s26
	global_load_lds_dwordx4 v[206:207], off
	v_lshl_add_u64 v[206:207], v[142:143], 0, s[22:23]
	s_mov_b32 m0, s77
	v_lshl_add_u64 v[142:143], v[142:143], 0, s[36:37]
	global_load_lds_dwordx4 v[206:207], off
	s_add_i32 m0, s77, 0x2000
	s_nop 0
	global_load_lds_dwordx4 v[142:143], off
	v_lshl_add_u64 v[142:143], v[154:155], 0, s[16:17]
	s_mov_b32 m0, s67
	s_nop 0
	global_load_lds_dwordx4 v[142:143], off
	v_lshl_add_u64 v[142:143], v[154:155], 0, s[20:21]
	s_mov_b32 m0, s69
	s_nop 0
	global_load_lds_dwordx4 v[142:143], off
	s_waitcnt vmcnt(8)
	s_waitcnt lgkmcnt(0)
	s_barrier
	s_waitcnt lgkmcnt(0)
	v_mfma_f32_16x16x32_bf16 v[60:63], v[130:133], v[182:185], v[60:63]
	v_mfma_f32_16x16x32_bf16 v[56:59], v[138:141], v[182:185], v[56:59]
	v_mfma_f32_16x16x32_bf16 v[52:55], v[130:133], v[190:193], v[52:55]
	v_mfma_f32_16x16x32_bf16 v[44:47], v[138:141], v[190:193], v[44:47]
	s_add_i32 s76, s76, 2
	v_mfma_f32_16x16x32_bf16 v[36:39], v[130:133], v[198:201], v[36:39]
	s_add_u32 s28, s28, 0x40000
	v_mfma_f32_16x16x32_bf16 v[28:31], v[138:141], v[198:201], v[28:31]
	s_addc_u32 s29, s29, 0
	v_mfma_f32_16x16x32_bf16 v[20:23], v[130:133], v[210:213], v[20:23]
	s_add_u32 s72, s72, 0x800000
	v_mfma_f32_16x16x32_bf16 v[12:15], v[138:141], v[210:213], v[12:15]
	s_addc_u32 s73, s73, 0
	v_mfma_f32_16x16x32_bf16 v[60:63], v[134:137], v[186:189], v[60:63]
	s_cmp_gt_u32 s76, 29
	v_mfma_f32_16x16x32_bf16 v[56:59], v[162:165], v[186:189], v[56:59]
	v_mfma_f32_16x16x32_bf16 v[52:55], v[134:137], v[194:197], v[52:55]
	v_mfma_f32_16x16x32_bf16 v[44:47], v[162:165], v[194:197], v[44:47]
	v_mfma_f32_16x16x32_bf16 v[36:39], v[134:137], v[202:205], v[36:39]
	v_mfma_f32_16x16x32_bf16 v[28:31], v[162:165], v[202:205], v[28:31]
	v_mfma_f32_16x16x32_bf16 v[20:23], v[134:137], v[214:217], v[20:23]
	v_mfma_f32_16x16x32_bf16 v[12:15], v[162:165], v[214:217], v[12:15]
	v_mfma_f32_16x16x32_bf16 v[48:51], v[166:169], v[182:185], v[48:51]
	v_mfma_f32_16x16x32_bf16 v[40:43], v[174:177], v[182:185], v[40:43]
	v_mfma_f32_16x16x32_bf16 v[32:35], v[166:169], v[190:193], v[32:35]
	v_mfma_f32_16x16x32_bf16 v[24:27], v[174:177], v[190:193], v[24:27]
	v_mfma_f32_16x16x32_bf16 v[16:19], v[166:169], v[198:201], v[16:19]
	v_mfma_f32_16x16x32_bf16 v[8:11], v[174:177], v[198:201], v[8:11]
	v_mfma_f32_16x16x32_bf16 v[4:7], v[166:169], v[210:213], v[4:7]
	v_mfma_f32_16x16x32_bf16 v[0:3], v[174:177], v[210:213], v[0:3]
	v_mfma_f32_16x16x32_bf16 v[48:51], v[170:173], v[186:189], v[48:51]
	v_mfma_f32_16x16x32_bf16 v[40:43], v[178:181], v[186:189], v[40:43]
	v_mfma_f32_16x16x32_bf16 v[32:35], v[170:173], v[194:197], v[32:35]
	v_mfma_f32_16x16x32_bf16 v[24:27], v[178:181], v[194:197], v[24:27]
	v_mfma_f32_16x16x32_bf16 v[16:19], v[170:173], v[202:205], v[16:19]
	v_mfma_f32_16x16x32_bf16 v[8:11], v[178:181], v[202:205], v[8:11]
	v_mfma_f32_16x16x32_bf16 v[4:7], v[170:173], v[214:217], v[4:7]
	v_mfma_f32_16x16x32_bf16 v[0:3], v[178:181], v[214:217], v[0:3]
	s_barrier
	s_cbranch_scc0 .LBB0_770
	s_and_b64 vcc, exec, s[38:39]
	s_cbranch_vccz .LBB0_773
	s_barrier
